# sc1 write-through also on P4's 8-byte bf16 row stores (U), on top of the LN f32 row-store write-through
# speedup vs baseline: 1.0065x; 1.0019x over previous
.LBB0_359:
	v_add_f32_e32 v130, v126, v127
	v_add_f32_e32 v131, v128, v129
	v_add_f32_e32 v130, v130, v131
	v_and_b32_e32 v131, 64, v243
	v_add_u32_e32 v131, 64, v131
	v_xor_b32_e32 v132, 1, v243
	v_cmp_lt_i32_e32 vcc, v132, v131
	v_add_f32_e32 v130, v244, v130
	v_lshlrev_b32_e32 v192, 4, v1
	v_cndmask_b32_e32 v132, v243, v132, vcc
	v_lshlrev_b32_e32 v202, 2, v132
	ds_bpermute_b32 v132, v202, v130
	s_and_b32 s2, s69, 0xffff8000
	s_add_i32 s2, s2, 0x8000
	s_waitcnt lgkmcnt(0)
	v_add_f32_e32 v130, v130, v132
	v_xor_b32_e32 v132, 2, v243
	v_cmp_lt_i32_e32 vcc, v132, v131
	s_nop 1
	v_cndmask_b32_e32 v132, v243, v132, vcc
	v_lshlrev_b32_e32 v203, 2, v132
	ds_bpermute_b32 v132, v203, v130
	s_waitcnt lgkmcnt(0)
	v_add_f32_e32 v130, v130, v132
	v_xor_b32_e32 v132, 4, v243
	v_cmp_lt_i32_e32 vcc, v132, v131
	s_nop 1
	v_cndmask_b32_e32 v132, v243, v132, vcc
	v_lshlrev_b32_e32 v204, 2, v132
	ds_bpermute_b32 v132, v204, v130
	s_waitcnt lgkmcnt(0)
	v_add_f32_e32 v130, v130, v132
	v_xor_b32_e32 v132, 8, v243
	v_cmp_lt_i32_e32 vcc, v132, v131
	s_nop 1
	v_cndmask_b32_e32 v132, v243, v132, vcc
	v_lshlrev_b32_e32 v205, 2, v132
	ds_bpermute_b32 v132, v205, v130
	s_waitcnt lgkmcnt(0)
	v_add_f32_e32 v130, v130, v132
	v_xor_b32_e32 v132, 16, v243
	v_cmp_lt_i32_e32 vcc, v132, v131
	s_nop 1
	v_cndmask_b32_e32 v132, v243, v132, vcc
	v_lshlrev_b32_e32 v206, 2, v132
	ds_bpermute_b32 v132, v206, v130
	s_waitcnt lgkmcnt(0)
	v_add_f32_e32 v130, v130, v132
	v_xor_b32_e32 v132, 32, v243
	v_cmp_lt_i32_e32 vcc, v132, v131
	s_nop 1
	v_cndmask_b32_e32 v131, v243, v132, vcc
	v_lshlrev_b32_e32 v207, 2, v131
	ds_bpermute_b32 v131, v207, v130
	s_waitcnt lgkmcnt(0)
	v_add_f32_e32 v144, v130, v131
	v_fmamk_f32 v143, v144, 0xb9800000, v87
	v_fmamk_f32 v142, v144, 0xb9800000, v86
	v_fmamk_f32 v89, v144, 0xb9800000, v89
	v_fmac_f32_e32 v88, 0xb9800000, v144
	v_pk_mul_f32 v[86:87], v[88:89], v[88:89]
	v_pk_mul_f32 v[130:131], v[142:143], v[142:143]
	v_fmamk_f32 v141, v144, 0xb9800000, v79
	v_pk_mov_b32 v[132:133], v[130:131], v[86:87] op_sel:[1,0]
	v_mov_b32_e32 v131, v87
	v_fmamk_f32 v140, v144, 0xb9800000, v78
	v_fmamk_f32 v81, v144, 0xb9800000, v81
	v_fmac_f32_e32 v80, 0xb9800000, v144
	v_fmamk_f32 v138, v144, 0xb9800000, v74
	v_pk_add_f32 v[86:87], v[132:133], v[130:131]
	v_pk_mul_f32 v[78:79], v[80:81], v[80:81]
	v_pk_mul_f32 v[130:131], v[140:141], v[140:141]
	v_fmamk_f32 v139, v144, 0xb9800000, v75
	v_mul_f32_e32 v74, v138, v138
	v_pk_mov_b32 v[132:133], v[130:131], v[78:79] op_sel:[1,0]
	v_mov_b32_e32 v131, v79
	v_fmac_f32_e32 v76, 0xb9800000, v144
	v_pk_fma_f32 v[74:75], v[138:139], v[138:139], v[74:75] op_sel_hi:[1,1,0]
	v_pk_add_f32 v[78:79], v[132:133], v[130:131]
	v_fmamk_f32 v77, v144, 0xb9800000, v77
	v_mul_f32_e32 v74, v76, v76
	v_pk_add_f32 v[86:87], v[86:87], v[86:87] op_sel_hi:[0,1]
	v_pk_add_f32 v[78:79], v[78:79], v[78:79] op_sel_hi:[0,1]
	v_pk_fma_f32 v[130:131], v[76:77], v[76:77], v[74:75] op_sel_hi:[1,1,0]
	v_fmamk_f32 v137, v144, 0xb9800000, v85
	v_fmamk_f32 v136, v144, 0xb9800000, v84
	v_fmamk_f32 v83, v144, 0xb9800000, v83
	v_fmac_f32_e32 v82, 0xb9800000, v144
	v_mul_f32_e32 v74, v82, v82
	v_mul_f32_e32 v130, v83, v83
	v_mul_f32_e32 v86, v136, v136
	v_mul_f32_e32 v78, v137, v137
	v_pk_add_f32 v[74:75], v[74:75], v[130:131]
	v_pk_add_f32 v[78:79], v[86:87], v[78:79]
	v_fmamk_f32 v135, v144, 0xb9800000, v71
	v_fmamk_f32 v134, v144, 0xb9800000, v70
	v_fmamk_f32 v73, v144, 0xb9800000, v73
	v_fmac_f32_e32 v72, 0xb9800000, v144
	v_fmamk_f32 v132, v144, 0xb9800000, v66
	v_pk_add_f32 v[74:75], v[74:75], v[78:79]
	v_pk_mul_f32 v[70:71], v[72:73], v[72:73]
	v_pk_mul_f32 v[78:79], v[134:135], v[134:135]
	v_fmamk_f32 v133, v144, 0xb9800000, v67
	v_mul_f32_e32 v66, v132, v132
	v_pk_mov_b32 v[84:85], v[78:79], v[70:71] op_sel:[1,0]
	v_mov_b32_e32 v79, v71
	v_fmac_f32_e32 v68, 0xb9800000, v144
	v_pk_fma_f32 v[66:67], v[132:133], v[132:133], v[66:67] op_sel_hi:[1,1,0]
	v_pk_add_f32 v[70:71], v[84:85], v[78:79]
	v_fmamk_f32 v69, v144, 0xb9800000, v69
	v_mul_f32_e32 v66, v68, v68
	v_pk_add_f32 v[74:75], v[74:75], v[74:75] op_sel_hi:[0,1]
	v_pk_add_f32 v[70:71], v[70:71], v[70:71] op_sel_hi:[0,1]
	v_pk_fma_f32 v[78:79], v[68:69], v[68:69], v[66:67] op_sel_hi:[1,1,0]
	v_fmamk_f32 v131, v144, 0xb9800000, v93
	v_fmamk_f32 v130, v144, 0xb9800000, v92
	v_fmamk_f32 v91, v144, 0xb9800000, v91
	v_fmac_f32_e32 v90, 0xb9800000, v144
	v_mul_f32_e32 v66, v90, v90
	v_mul_f32_e32 v78, v91, v91
	v_mul_f32_e32 v70, v130, v130
	v_mul_f32_e32 v74, v131, v131
	v_pk_add_f32 v[66:67], v[66:67], v[78:79]
	v_pk_add_f32 v[70:71], v[70:71], v[74:75]
	v_fmamk_f32 v201, v144, 0xb9800000, v95
	v_pk_add_f32 v[66:67], v[66:67], v[70:71]
	v_fmamk_f32 v200, v144, 0xb9800000, v94
	v_fmamk_f32 v97, v144, 0xb9800000, v97
	v_fmac_f32_e32 v96, 0xb9800000, v144
	v_pk_add_f32 v[66:67], v[66:67], v[66:67] op_sel_hi:[0,1]
	v_pk_mul_f32 v[70:71], v[96:97], v[96:97]
	v_pk_mul_f32 v[74:75], v[200:201], v[200:201]
	v_fmamk_f32 v94, v144, 0xb9800000, v98
	v_pk_mov_b32 v[78:79], v[74:75], v[70:71] op_sel:[1,0]
	v_mov_b32_e32 v75, v71
	v_fmamk_f32 v95, v144, 0xb9800000, v99
	v_fmac_f32_e32 v100, 0xb9800000, v144
	v_mul_f32_e32 v66, v94, v94
	v_pk_add_f32 v[70:71], v[78:79], v[74:75]
	v_fmamk_f32 v101, v144, 0xb9800000, v101
	v_pk_fma_f32 v[74:75], v[94:95], v[94:95], v[66:67] op_sel_hi:[1,1,0]
	v_mul_f32_e32 v66, v100, v100
	v_pk_add_f32 v[70:71], v[70:71], v[70:71] op_sel_hi:[0,1]
	v_pk_fma_f32 v[78:79], v[100:101], v[100:101], v[66:67] op_sel_hi:[1,1,0]
	v_fmamk_f32 v93, v144, 0xb9800000, v113
	v_fmamk_f32 v92, v144, 0xb9800000, v112
	v_fmamk_f32 v111, v144, 0xb9800000, v111
	v_fmac_f32_e32 v110, 0xb9800000, v144
	v_mul_f32_e32 v74, v110, v110
	v_mul_f32_e32 v78, v111, v111
	v_mul_f32_e32 v70, v92, v92
	v_mul_f32_e32 v66, v93, v93
	v_pk_add_f32 v[74:75], v[74:75], v[78:79]
	v_pk_add_f32 v[66:67], v[70:71], v[66:67]
	v_fmamk_f32 v87, v144, 0xb9800000, v107
	v_pk_add_f32 v[66:67], v[74:75], v[66:67]
	v_fmamk_f32 v86, v144, 0xb9800000, v106
	v_fmamk_f32 v109, v144, 0xb9800000, v109
	v_fmac_f32_e32 v108, 0xb9800000, v144
	v_pk_add_f32 v[66:67], v[66:67], v[66:67] op_sel_hi:[0,1]
	v_pk_mul_f32 v[70:71], v[108:109], v[108:109]
	v_pk_mul_f32 v[74:75], v[86:87], v[86:87]
	v_fmamk_f32 v84, v144, 0xb9800000, v102
	v_pk_mov_b32 v[78:79], v[74:75], v[70:71] op_sel:[1,0]
	v_mov_b32_e32 v75, v71
	v_fmamk_f32 v85, v144, 0xb9800000, v103
	v_fmac_f32_e32 v104, 0xb9800000, v144
	v_mul_f32_e32 v66, v84, v84
	v_pk_add_f32 v[70:71], v[78:79], v[74:75]
	v_fmamk_f32 v105, v144, 0xb9800000, v105
	v_pk_fma_f32 v[74:75], v[84:85], v[84:85], v[66:67] op_sel_hi:[1,1,0]
	v_mul_f32_e32 v66, v104, v104
	v_pk_add_f32 v[70:71], v[70:71], v[70:71] op_sel_hi:[0,1]
	v_pk_fma_f32 v[98:99], v[104:105], v[104:105], v[66:67] op_sel_hi:[1,1,0]
	v_fmamk_f32 v79, v144, 0xb9800000, v125
	v_fmamk_f32 v78, v144, 0xb9800000, v124
	v_fmamk_f32 v123, v144, 0xb9800000, v123
	v_fmac_f32_e32 v122, 0xb9800000, v144
	v_mul_f32_e32 v74, v122, v122
	v_mul_f32_e32 v98, v123, v123
	v_mul_f32_e32 v70, v78, v78
	v_mul_f32_e32 v66, v79, v79
	v_pk_add_f32 v[74:75], v[74:75], v[98:99]
	v_pk_add_f32 v[66:67], v[70:71], v[66:67]
	v_fmamk_f32 v117, v144, 0xb9800000, v117
	v_pk_add_f32 v[66:67], v[74:75], v[66:67]
	v_fmamk_f32 v75, v144, 0xb9800000, v115
	v_fmamk_f32 v74, v144, 0xb9800000, v114
	v_fmac_f32_e32 v116, 0xb9800000, v144
	v_pk_add_f32 v[98:99], v[66:67], v[66:67] op_sel_hi:[0,1]
	v_pk_mul_f32 v[66:67], v[116:117], v[116:117]
	v_pk_mul_f32 v[70:71], v[74:75], v[74:75]
	v_fmac_f32_e32 v120, 0xb9800000, v144
	v_pk_mov_b32 v[102:103], v[70:71], v[66:67] op_sel:[1,0]
	v_mov_b32_e32 v71, v67
	v_pk_add_f32 v[66:67], v[102:103], v[70:71]
	v_fmamk_f32 v70, v144, 0xb9800000, v118
	v_pk_add_f32 v[102:103], v[66:67], v[66:67] op_sel_hi:[0,1]
	v_fmamk_f32 v71, v144, 0xb9800000, v119
	v_mul_f32_e32 v66, v70, v70
	v_fmamk_f32 v121, v144, 0xb9800000, v121
	v_pk_fma_f32 v[106:107], v[70:71], v[70:71], v[66:67] op_sel_hi:[1,1,0]
	v_mul_f32_e32 v66, v120, v120
	v_pk_fma_f32 v[112:113], v[120:121], v[120:121], v[66:67] op_sel_hi:[1,1,0]
	v_fmamk_f32 v67, v144, 0xb9800000, v129
	v_fmamk_f32 v66, v144, 0xb9800000, v128
	v_fmamk_f32 v127, v144, 0xb9800000, v127
	v_fmac_f32_e32 v126, 0xb9800000, v144
	v_mul_f32_e32 v106, v126, v126
	v_mul_f32_e32 v112, v127, v127
	v_mul_f32_e32 v102, v66, v66
	v_mul_f32_e32 v98, v67, v67
	v_pk_add_f32 v[106:107], v[106:107], v[112:113]
	v_pk_add_f32 v[98:99], v[102:103], v[98:99]
	ds_read_b128 v[112:115], v241
	ds_read_b128 v[144:147], v241 offset:16384
	v_pk_add_f32 v[98:99], v[106:107], v[98:99]
	ds_read_b128 v[148:151], v241 offset:17408
	ds_read_b128 v[208:211], v241 offset:1024
	v_add_f32_e32 v98, v98, v99
	ds_bpermute_b32 v99, v202, v98
	s_waitcnt lgkmcnt(0)
	v_add_f32_e32 v98, v98, v99
	ds_bpermute_b32 v99, v203, v98
	s_waitcnt lgkmcnt(0)
	v_add_f32_e32 v98, v98, v99
	ds_bpermute_b32 v99, v204, v98
	s_waitcnt lgkmcnt(0)
	v_add_f32_e32 v98, v98, v99
	ds_bpermute_b32 v99, v205, v98
	s_waitcnt lgkmcnt(0)
	v_add_f32_e32 v98, v98, v99
	ds_bpermute_b32 v99, v206, v98
	s_waitcnt lgkmcnt(0)
	v_add_f32_e32 v98, v98, v99
	ds_bpermute_b32 v99, v207, v98
	s_waitcnt lgkmcnt(0)
	v_add_f32_e32 v98, v98, v99
	v_fmamk_f32 v98, v98, 0x39800000, v179
	v_mul_f32_e32 v99, 0x4f800000, v98
	v_cmp_gt_f32_e32 vcc, s79, v98
	s_nop 1
	v_cndmask_b32_e32 v98, v98, v99, vcc
	v_sqrt_f32_e32 v99, v98
	s_nop 0
	v_add_u32_e32 v102, -1, v99
	v_fma_f32 v103, -v102, v99, v98
	v_cmp_ge_f32_e64 s[0:1], 0, v103
	v_add_u32_e32 v103, 1, v99
	s_nop 0
	v_cndmask_b32_e64 v102, v99, v102, s[0:1]
	v_fma_f32 v99, -v103, v99, v98
	v_cmp_lt_f32_e64 s[0:1], 0, v99
	s_nop 1
	v_cndmask_b32_e64 v99, v102, v103, s[0:1]
	v_mul_f32_e32 v102, 0x37800000, v99
	v_cndmask_b32_e32 v99, v99, v102, vcc
	v_cmp_class_f32_e32 vcc, v98, v242
	s_nop 1
	v_cndmask_b32_e32 v98, v99, v98, vcc
	v_div_scale_f32 v99, s[0:1], v98, v98, 1.0
	v_rcp_f32_e32 v102, v99
	s_nop 0
	v_fma_f32 v103, -v99, v102, 1.0
	v_fmac_f32_e32 v102, v103, v102
	v_div_scale_f32 v103, vcc, 1.0, v98, 1.0
	v_mul_f32_e32 v106, v103, v102
	v_fma_f32 v107, -v99, v106, v103
	v_fmac_f32_e32 v106, v107, v102
	v_fma_f32 v99, -v99, v106, v103
	v_div_fmas_f32 v99, v99, v102, v106
	v_div_fixup_f32 v102, v99, v98, 1.0
	v_pk_mul_f32 v[88:89], v[88:89], v[102:103] op_sel_hi:[1,0]
	v_pk_mul_f32 v[106:107], v[142:143], v[102:103] op_sel_hi:[1,0]
	v_pk_fma_f32 v[154:155], v[114:115], v[88:89], v[146:147]
	v_pk_fma_f32 v[152:153], v[112:113], v[106:107], v[144:145]
	v_mov_b32_e32 v107, v155
	v_pk_mov_b32 v[88:89], v[152:153], v[154:155] op_sel:[1,0]
	v_mov_b32_e32 v106, v152
	v_pk_add_f32 v[88:89], v[88:89], v[106:107]
	v_pk_mul_f32 v[80:81], v[80:81], v[102:103] op_sel_hi:[1,0]
	v_pk_mul_f32 v[106:107], v[140:141], v[102:103] op_sel_hi:[1,0]
	v_pk_fma_f32 v[150:151], v[210:211], v[80:81], v[150:151]
	v_pk_fma_f32 v[148:149], v[208:209], v[106:107], v[148:149]
	global_store_dwordx4 v192, v[152:155], s[54:55] sc1 nt
	global_store_dwordx4 v192, v[148:151], s[54:55] offset:1024 sc1 nt
	ds_read_b128 v[112:115], v241 offset:18432
	ds_read_b128 v[140:143], v241 offset:2048
	ds_read_b128 v[208:211], v241 offset:19456
	ds_read_b128 v[212:215], v241 offset:3072
	v_pk_mov_b32 v[80:81], v[148:149], v[150:151] op_sel:[1,0]
	v_mov_b32_e32 v106, v148
	v_mov_b32_e32 v107, v151
	v_pk_add_f32 v[80:81], v[80:81], v[106:107]
	v_pk_mul_f32 v[106:107], v[138:139], v[102:103] op_sel_hi:[1,0]
	v_pk_mul_f32 v[76:77], v[76:77], v[102:103] op_sel_hi:[1,0]
	s_waitcnt lgkmcnt(2)
	v_pk_fma_f32 v[144:145], v[140:141], v[106:107], v[112:113]
	v_pk_mul_f32 v[82:83], v[82:83], v[102:103] op_sel_hi:[1,0]
	v_pk_mul_f32 v[112:113], v[136:137], v[102:103] op_sel_hi:[1,0]
	v_add_f32_e32 v88, v88, v89
	v_pk_add_f32 v[80:81], v[80:81], v[80:81] op_sel_hi:[0,1]
	v_pk_fma_f32 v[146:147], v[142:143], v[76:77], v[114:115]
	s_waitcnt lgkmcnt(0)
	v_pk_fma_f32 v[142:143], v[214:215], v[112:113], v[210:211]
	v_pk_fma_f32 v[140:141], v[212:213], v[82:83], v[208:209]
	v_add_f32_e32 v89, 0, v88
	global_store_dwordx4 v192, v[144:147], s[54:55] offset:2048 sc1 nt
	v_add_f32_e32 v77, v144, v145
	v_add_f32_e32 v107, v146, v147
	global_store_dwordx4 v192, v[140:143], s[54:55] offset:3072 sc1 nt
	v_mov_b32_e32 v76, v140
	v_mov_b32_e32 v106, v141
	v_mov_b32_e32 v80, v142
	v_mov_b32_e32 v88, v143
	v_pk_add_f32 v[76:77], v[76:77], v[106:107]
	v_pk_add_f32 v[80:81], v[80:81], v[88:89]
	v_pk_mul_f32 v[88:89], v[134:135], v[102:103] op_sel_hi:[1,0]
	v_pk_add_f32 v[76:77], v[76:77], v[80:81]
	ds_read_b128 v[80:83], v241 offset:4096
	ds_read_b128 v[112:115], v241 offset:20480
	v_pk_mul_f32 v[72:73], v[72:73], v[102:103] op_sel_hi:[1,0]
	ds_read_b128 v[208:211], v241 offset:21504
	ds_read_b128 v[212:215], v241 offset:5120
	v_lshl_add_u64 v[98:99], s[54:55], 0, v[192:193]
	v_pk_mul_f32 v[68:69], v[68:69], v[102:103] op_sel_hi:[1,0]
	s_waitcnt lgkmcnt(2)
	v_pk_fma_f32 v[138:139], v[82:83], v[72:73], v[114:115]
	v_pk_fma_f32 v[136:137], v[80:81], v[88:89], v[112:113]
	v_add_co_u32_e32 v72, vcc, s77, v98
	v_pk_mov_b32 v[80:81], v[136:137], v[138:139] op_sel:[1,0]
	v_mov_b32_e32 v82, v136
	v_mov_b32_e32 v83, v139
	v_addc_co_u32_e32 v73, vcc, 0, v99, vcc
	v_pk_add_f32 v[80:81], v[80:81], v[82:83]
	v_add_co_u32_e32 v118, vcc, s75, v98
	v_pk_add_f32 v[106:107], v[80:81], v[80:81] op_sel_hi:[0,1]
	v_pk_mul_f32 v[80:81], v[132:133], v[102:103] op_sel_hi:[1,0]
	v_addc_co_u32_e32 v119, vcc, 0, v99, vcc
	s_waitcnt lgkmcnt(0)
	v_pk_fma_f32 v[134:135], v[214:215], v[68:69], v[210:211]
	v_pk_fma_f32 v[132:133], v[212:213], v[80:81], v[208:209]
	global_store_dwordx4 v[118:119], v[136:139], off offset:-4096 sc1 nt
	global_store_dwordx4 v[72:73], v[132:135], off offset:1024 sc1 nt
	ds_read_b128 v[80:83], v241 offset:22528
	ds_read_b128 v[112:115], v241 offset:6144
	v_pk_mul_f32 v[128:129], v[90:91], v[102:103] op_sel_hi:[1,0]
	v_pk_mul_f32 v[130:131], v[130:131], v[102:103] op_sel_hi:[1,0]
	ds_read_b128 v[88:91], v241 offset:23552
	ds_read_b128 v[208:211], v241 offset:7168
	v_pk_add_f32 v[76:77], v[76:77], v[76:77] op_sel_hi:[0,1]
	s_waitcnt lgkmcnt(2)
	v_pk_fma_f32 v[130:131], v[114:115], v[130:131], v[82:83]
	v_pk_fma_f32 v[128:129], v[112:113], v[128:129], v[80:81]
	v_add_f32_e32 v69, v132, v133
	v_add_f32_e32 v125, v134, v135
	v_mov_b32_e32 v68, v128
	v_mov_b32_e32 v124, v129
	v_mov_b32_e32 v106, v130
	v_mov_b32_e32 v76, v131
	v_pk_add_f32 v[68:69], v[68:69], v[124:125]
	v_pk_add_f32 v[76:77], v[106:107], v[76:77]
	v_pk_mul_f32 v[80:81], v[96:97], v[102:103] op_sel_hi:[1,0]
	v_pk_add_f32 v[68:69], v[68:69], v[76:77]
	v_pk_mul_f32 v[76:77], v[200:201], v[102:103] op_sel_hi:[1,0]
	s_waitcnt lgkmcnt(0)
	v_pk_fma_f32 v[114:115], v[210:211], v[80:81], v[90:91]
	v_pk_fma_f32 v[112:113], v[208:209], v[76:77], v[88:89]
	global_store_dwordx4 v[72:73], v[128:131], off offset:2048 sc1 nt
	global_store_dwordx4 v[72:73], v[112:115], off offset:3072 sc1 nt
	ds_read_b128 v[80:83], v241 offset:8192
	ds_read_b128 v[88:91], v241 offset:24576
	ds_read_b128 v[208:211], v241 offset:25600
	ds_read_b128 v[212:215], v241 offset:9216
	v_pk_mov_b32 v[72:73], v[112:113], v[114:115] op_sel:[1,0]
	v_mov_b32_e32 v76, v112
	v_mov_b32_e32 v77, v115
	v_pk_add_f32 v[72:73], v[72:73], v[76:77]
	v_pk_mul_f32 v[76:77], v[94:95], v[102:103] op_sel_hi:[1,0]
	v_pk_mul_f32 v[94:95], v[100:101], v[102:103] op_sel_hi:[1,0]
	v_pk_add_f32 v[68:69], v[68:69], v[68:69] op_sel_hi:[0,1]
	s_waitcnt lgkmcnt(2)
	v_pk_fma_f32 v[96:97], v[82:83], v[94:95], v[90:91]
	v_pk_fma_f32 v[94:95], v[80:81], v[76:77], v[88:89]
	v_pk_mul_f32 v[82:83], v[110:111], v[102:103] op_sel_hi:[1,0]
	v_pk_mul_f32 v[88:89], v[92:93], v[102:103] op_sel_hi:[1,0]
	s_waitcnt lgkmcnt(0)
	v_pk_fma_f32 v[90:91], v[212:213], v[82:83], v[208:209]
	v_pk_fma_f32 v[92:93], v[214:215], v[88:89], v[210:211]
	global_store_dwordx4 v[118:119], v[94:97], off sc1 nt
	v_add_f32_e32 v77, v94, v95
	v_add_f32_e32 v81, v96, v97
	global_store_dwordx4 v[118:119], v[90:93], off offset:1024 sc1 nt
	v_mov_b32_e32 v76, v90
	v_mov_b32_e32 v80, v91
	v_pk_add_f32 v[72:73], v[72:73], v[72:73] op_sel_hi:[0,1]
	v_pk_add_f32 v[76:77], v[76:77], v[80:81]
	ds_read_b128 v[80:83], v241 offset:26624
	ds_read_b128 v[208:211], v241 offset:10240
	v_mov_b32_e32 v72, v92
	v_mov_b32_e32 v68, v93
	v_pk_add_f32 v[68:69], v[72:73], v[68:69]
	v_pk_mul_f32 v[72:73], v[86:87], v[102:103] op_sel_hi:[1,0]
	v_pk_add_f32 v[68:69], v[76:77], v[68:69]
	v_pk_mul_f32 v[76:77], v[108:109], v[102:103] op_sel_hi:[1,0]
	ds_read_b128 v[106:109], v241 offset:27648
	ds_read_b128 v[212:215], v241 offset:11264
	s_waitcnt lgkmcnt(2)
	v_pk_fma_f32 v[88:89], v[76:77], v[210:211], v[82:83]
	v_pk_fma_f32 v[86:87], v[72:73], v[208:209], v[80:81]
	v_mov_b32_e32 v77, v89
	v_pk_mov_b32 v[72:73], v[86:87], v[88:89] op_sel:[1,0]
	v_mov_b32_e32 v76, v86
	v_pk_add_f32 v[72:73], v[72:73], v[76:77]
	v_pk_mul_f32 v[76:77], v[84:85], v[102:103] op_sel_hi:[1,0]
	v_pk_mul_f32 v[80:81], v[104:105], v[102:103] op_sel_hi:[1,0]
	s_waitcnt lgkmcnt(0)
	v_pk_fma_f32 v[82:83], v[76:77], v[212:213], v[106:107]
	v_pk_fma_f32 v[84:85], v[80:81], v[214:215], v[108:109]
	global_store_dwordx4 v[118:119], v[86:89], off offset:2048 sc1 nt
	global_store_dwordx4 v[118:119], v[82:85], off offset:3072 sc1 nt
	ds_read_b128 v[104:107], v241 offset:12288
	ds_read_b128 v[108:111], v241 offset:28672
	v_pk_mul_f32 v[118:119], v[122:123], v[102:103] op_sel_hi:[1,0]
	v_pk_mul_f32 v[78:79], v[78:79], v[102:103] op_sel_hi:[1,0]
	v_pk_add_f32 v[68:69], v[68:69], v[68:69] op_sel_hi:[0,1]
	v_pk_add_f32 v[72:73], v[72:73], v[72:73] op_sel_hi:[0,1]
	ds_read_b128 v[122:125], v241 offset:29696
	ds_read_b128 v[208:211], v241 offset:13312
	s_waitcnt lgkmcnt(2)
	v_pk_fma_f32 v[80:81], v[78:79], v[106:107], v[110:111]
	v_pk_fma_f32 v[78:79], v[118:119], v[104:105], v[108:109]
	v_add_f32_e32 v77, v82, v83
	v_add_f32_e32 v101, v84, v85
	v_mov_b32_e32 v76, v78
	v_mov_b32_e32 v100, v79
	v_mov_b32_e32 v72, v80
	v_mov_b32_e32 v68, v81
	v_pk_add_f32 v[76:77], v[76:77], v[100:101]
	v_pk_add_f32 v[68:69], v[72:73], v[68:69]
	v_pk_mul_f32 v[72:73], v[116:117], v[102:103] op_sel_hi:[1,0]
	v_pk_add_f32 v[68:69], v[76:77], v[68:69]
	s_waitcnt lgkmcnt(0)
	v_pk_fma_f32 v[76:77], v[72:73], v[210:211], v[124:125]
	v_pk_add_f32 v[100:101], v[68:69], v[68:69] op_sel:[0,1] op_sel_hi:[1,0]
	v_pk_mul_f32 v[68:69], v[74:75], v[102:103] op_sel_hi:[1,0]
	v_mov_b32_e32 v73, v77
	v_pk_fma_f32 v[74:75], v[68:69], v[208:209], v[122:123]
	ds_read_b128 v[104:107], v241 offset:30720
	ds_read_b128 v[108:111], v241 offset:14336
	v_pk_mov_b32 v[68:69], v[74:75], v[76:77] op_sel:[1,0]
	v_mov_b32_e32 v72, v74
	v_pk_add_f32 v[68:69], v[68:69], v[72:73]
	v_pk_mul_f32 v[66:67], v[66:67], v[102:103] op_sel_hi:[1,0]
	v_pk_add_f32 v[124:125], v[68:69], v[68:69] op_sel:[0,1] op_sel_hi:[1,0]
	v_pk_mul_f32 v[68:69], v[70:71], v[102:103] op_sel_hi:[1,0]
	v_pk_mul_f32 v[70:71], v[120:121], v[102:103] op_sel_hi:[1,0]
	ds_read_b128 v[116:119], v241 offset:31744
	ds_read_b128 v[120:123], v241 offset:15360
	s_waitcnt lgkmcnt(2)
	v_pk_fma_f32 v[72:73], v[70:71], v[110:111], v[106:107]
	v_pk_fma_f32 v[70:71], v[68:69], v[108:109], v[104:105]
	v_pk_mul_f32 v[108:109], v[126:127], v[102:103] op_sel_hi:[1,0]
	v_add_f32_e32 v104, v70, v71
	s_waitcnt lgkmcnt(0)
	v_pk_fma_f32 v[68:69], v[66:67], v[122:123], v[118:119]
	v_pk_fma_f32 v[66:67], v[108:109], v[120:121], v[116:117]
	v_add_f32_e32 v106, v72, v73
	v_mov_b32_e32 v125, v66
	v_mov_b32_e32 v101, v67
	v_mov_b32_e32 v105, v68
	v_mov_b32_e32 v107, v69
	v_pk_add_f32 v[100:101], v[124:125], v[100:101]
	v_pk_add_f32 v[102:103], v[104:105], v[106:107]
	v_add_co_u32_e32 v98, vcc, s78, v98
	v_pk_add_f32 v[100:101], v[100:101], v[102:103]
	s_nop 0
	v_addc_co_u32_e32 v99, vcc, 0, v99, vcc
	v_add_f32_e32 v100, v100, v101
	ds_bpermute_b32 v101, v202, v100
	global_store_dwordx4 v[98:99], v[78:81], off sc1 nt
	global_store_dwordx4 v[98:99], v[74:77], off offset:1024 sc1 nt
	global_store_dwordx4 v[98:99], v[70:73], off offset:2048 sc1 nt
	global_store_dwordx4 v[98:99], v[66:69], off offset:3072 sc1 nt
	s_waitcnt lgkmcnt(0)
	v_add_f32_e32 v100, v100, v101
	ds_bpermute_b32 v101, v203, v100
	s_waitcnt lgkmcnt(0)
	v_add_f32_e32 v100, v100, v101
	ds_bpermute_b32 v101, v204, v100
	s_waitcnt lgkmcnt(0)
	v_add_f32_e32 v100, v100, v101
	ds_bpermute_b32 v101, v205, v100
	s_waitcnt lgkmcnt(0)
	v_add_f32_e32 v100, v100, v101
	ds_bpermute_b32 v101, v206, v100
	s_waitcnt lgkmcnt(0)
	v_add_f32_e32 v100, v100, v101
	ds_bpermute_b32 v101, v207, v100
	s_waitcnt lgkmcnt(0)
	v_add_f32_e32 v106, v100, v101
	v_fmamk_f32 v153, v106, 0xb9800000, v153
	v_fmac_f32_e32 v152, 0xb9800000, v106
	v_fmamk_f32 v155, v106, 0xb9800000, v155
	v_fmac_f32_e32 v154, 0xb9800000, v106
	v_pk_mul_f32 v[98:99], v[154:155], v[154:155]
	v_pk_mul_f32 v[100:101], v[152:153], v[152:153]
	v_fmamk_f32 v149, v106, 0xb9800000, v149
	v_pk_mov_b32 v[102:103], v[100:101], v[98:99] op_sel:[1,0]
	v_mov_b32_e32 v101, v99
	v_pk_add_f32 v[98:99], v[102:103], v[100:101]
	v_fmac_f32_e32 v148, 0xb9800000, v106
	v_fmamk_f32 v151, v106, 0xb9800000, v151
	v_fmac_f32_e32 v150, 0xb9800000, v106
	v_pk_add_f32 v[98:99], v[98:99], v[98:99] op_sel_hi:[0,1]
	v_pk_mul_f32 v[100:101], v[150:151], v[150:151]
	v_pk_mul_f32 v[102:103], v[148:149], v[148:149]
	v_fmac_f32_e32 v144, 0xb9800000, v106
	v_pk_mov_b32 v[104:105], v[102:103], v[100:101] op_sel:[1,0]
	v_mov_b32_e32 v103, v101
	v_fmamk_f32 v145, v106, 0xb9800000, v145
	v_fmac_f32_e32 v146, 0xb9800000, v106
	v_mul_f32_e32 v98, v144, v144
	v_pk_add_f32 v[100:101], v[104:105], v[102:103]
	v_fmamk_f32 v147, v106, 0xb9800000, v147
	v_pk_fma_f32 v[102:103], v[144:145], v[144:145], v[98:99] op_sel_hi:[1,1,0]
	v_mul_f32_e32 v98, v146, v146
	v_pk_add_f32 v[100:101], v[100:101], v[100:101] op_sel_hi:[0,1]
	v_pk_fma_f32 v[104:105], v[146:147], v[146:147], v[98:99] op_sel_hi:[1,1,0]
	v_fmamk_f32 v143, v106, 0xb9800000, v143
	v_fmac_f32_e32 v142, 0xb9800000, v106
	v_fmamk_f32 v141, v106, 0xb9800000, v141
	v_fmac_f32_e32 v140, 0xb9800000, v106
	v_mul_f32_e32 v102, v140, v140
	v_mul_f32_e32 v104, v141, v141
	v_mul_f32_e32 v98, v142, v142
	v_mul_f32_e32 v100, v143, v143
	v_pk_add_f32 v[102:103], v[102:103], v[104:105]
	v_pk_add_f32 v[98:99], v[98:99], v[100:101]
	v_fmamk_f32 v137, v106, 0xb9800000, v137
	v_pk_add_f32 v[98:99], v[102:103], v[98:99]
	v_fmac_f32_e32 v136, 0xb9800000, v106
	v_fmamk_f32 v139, v106, 0xb9800000, v139
	v_fmac_f32_e32 v138, 0xb9800000, v106
	v_pk_add_f32 v[98:99], v[98:99], v[98:99] op_sel_hi:[0,1]
	v_pk_mul_f32 v[100:101], v[138:139], v[138:139]
	v_pk_mul_f32 v[102:103], v[136:137], v[136:137]
	v_fmac_f32_e32 v132, 0xb9800000, v106
	v_pk_mov_b32 v[104:105], v[102:103], v[100:101] op_sel:[1,0]
	v_mov_b32_e32 v103, v101
	v_fmamk_f32 v133, v106, 0xb9800000, v133
	v_fmac_f32_e32 v134, 0xb9800000, v106
	v_mul_f32_e32 v98, v132, v132
	v_pk_add_f32 v[100:101], v[104:105], v[102:103]
	v_fmamk_f32 v135, v106, 0xb9800000, v135
	v_pk_fma_f32 v[102:103], v[132:133], v[132:133], v[98:99] op_sel_hi:[1,1,0]
	v_mul_f32_e32 v98, v134, v134
	v_pk_add_f32 v[100:101], v[100:101], v[100:101] op_sel_hi:[0,1]
	v_pk_fma_f32 v[104:105], v[134:135], v[134:135], v[98:99] op_sel_hi:[1,1,0]
	v_fmamk_f32 v131, v106, 0xb9800000, v131
	v_fmac_f32_e32 v130, 0xb9800000, v106
	v_fmamk_f32 v129, v106, 0xb9800000, v129
	v_fmac_f32_e32 v128, 0xb9800000, v106
	v_mul_f32_e32 v102, v128, v128
	v_mul_f32_e32 v104, v129, v129
	v_mul_f32_e32 v100, v130, v130
	v_mul_f32_e32 v98, v131, v131
	v_pk_add_f32 v[102:103], v[102:103], v[104:105]
	v_pk_add_f32 v[98:99], v[100:101], v[98:99]
	v_fmamk_f32 v113, v106, 0xb9800000, v113
	v_pk_add_f32 v[98:99], v[102:103], v[98:99]
	v_fmac_f32_e32 v112, 0xb9800000, v106
	v_fmamk_f32 v115, v106, 0xb9800000, v115
	v_fmac_f32_e32 v114, 0xb9800000, v106
	v_pk_add_f32 v[98:99], v[98:99], v[98:99] op_sel_hi:[0,1]
	v_pk_mul_f32 v[100:101], v[114:115], v[114:115]
	v_pk_mul_f32 v[102:103], v[112:113], v[112:113]
	v_fmac_f32_e32 v94, 0xb9800000, v106
	v_pk_mov_b32 v[104:105], v[102:103], v[100:101] op_sel:[1,0]
	v_mov_b32_e32 v103, v101
	v_fmamk_f32 v95, v106, 0xb9800000, v95
	v_fmac_f32_e32 v96, 0xb9800000, v106
	v_mul_f32_e32 v98, v94, v94
	v_pk_add_f32 v[100:101], v[104:105], v[102:103]
	v_fmamk_f32 v97, v106, 0xb9800000, v97
	v_pk_fma_f32 v[102:103], v[94:95], v[94:95], v[98:99] op_sel_hi:[1,1,0]
	v_mul_f32_e32 v98, v96, v96
	v_pk_add_f32 v[100:101], v[100:101], v[100:101] op_sel_hi:[0,1]
	v_pk_fma_f32 v[104:105], v[96:97], v[96:97], v[98:99] op_sel_hi:[1,1,0]
	v_fmamk_f32 v93, v106, 0xb9800000, v93
	v_fmac_f32_e32 v92, 0xb9800000, v106
	v_fmamk_f32 v91, v106, 0xb9800000, v91
	v_fmac_f32_e32 v90, 0xb9800000, v106
	v_mul_f32_e32 v102, v90, v90
	v_mul_f32_e32 v104, v91, v91
	v_mul_f32_e32 v100, v92, v92
	v_mul_f32_e32 v98, v93, v93
	v_pk_add_f32 v[102:103], v[102:103], v[104:105]
	v_pk_add_f32 v[98:99], v[100:101], v[98:99]
	v_fmamk_f32 v87, v106, 0xb9800000, v87
	v_pk_add_f32 v[98:99], v[102:103], v[98:99]
	v_fmac_f32_e32 v86, 0xb9800000, v106
	v_fmamk_f32 v89, v106, 0xb9800000, v89
	v_fmac_f32_e32 v88, 0xb9800000, v106
	v_pk_add_f32 v[98:99], v[98:99], v[98:99] op_sel_hi:[0,1]
	v_pk_mul_f32 v[100:101], v[88:89], v[88:89]
	v_pk_mul_f32 v[102:103], v[86:87], v[86:87]
	v_fmac_f32_e32 v82, 0xb9800000, v106
	v_pk_mov_b32 v[104:105], v[102:103], v[100:101] op_sel:[1,0]
	v_mov_b32_e32 v103, v101
	v_fmamk_f32 v83, v106, 0xb9800000, v83
	v_fmac_f32_e32 v84, 0xb9800000, v106
	v_mul_f32_e32 v98, v82, v82
	v_pk_add_f32 v[100:101], v[104:105], v[102:103]
	v_fmamk_f32 v85, v106, 0xb9800000, v85
	v_pk_fma_f32 v[102:103], v[82:83], v[82:83], v[98:99] op_sel_hi:[1,1,0]
	v_mul_f32_e32 v98, v84, v84
	v_pk_add_f32 v[100:101], v[100:101], v[100:101] op_sel_hi:[0,1]
	v_pk_fma_f32 v[104:105], v[84:85], v[84:85], v[98:99] op_sel_hi:[1,1,0]
	v_fmamk_f32 v81, v106, 0xb9800000, v81
	v_fmac_f32_e32 v80, 0xb9800000, v106
	v_fmamk_f32 v79, v106, 0xb9800000, v79
	v_fmac_f32_e32 v78, 0xb9800000, v106
	v_mul_f32_e32 v102, v78, v78
	v_mul_f32_e32 v104, v79, v79
	v_mul_f32_e32 v100, v80, v80
	v_mul_f32_e32 v98, v81, v81
	v_pk_add_f32 v[102:103], v[102:103], v[104:105]
	v_pk_add_f32 v[98:99], v[100:101], v[98:99]
	v_fmamk_f32 v75, v106, 0xb9800000, v75
	v_pk_add_f32 v[98:99], v[102:103], v[98:99]
	v_fmac_f32_e32 v74, 0xb9800000, v106
	v_fmamk_f32 v77, v106, 0xb9800000, v77
	v_fmac_f32_e32 v76, 0xb9800000, v106
	v_pk_add_f32 v[98:99], v[98:99], v[98:99] op_sel_hi:[0,1]
	v_pk_mul_f32 v[100:101], v[76:77], v[76:77]
	v_pk_mul_f32 v[102:103], v[74:75], v[74:75]
	v_fmac_f32_e32 v70, 0xb9800000, v106
	v_pk_mov_b32 v[104:105], v[102:103], v[100:101] op_sel:[1,0]
	v_mov_b32_e32 v103, v101
	v_fmamk_f32 v71, v106, 0xb9800000, v71
	v_fmac_f32_e32 v72, 0xb9800000, v106
	v_mul_f32_e32 v98, v70, v70
	v_pk_add_f32 v[100:101], v[104:105], v[102:103]
	v_fmamk_f32 v73, v106, 0xb9800000, v73
	v_pk_fma_f32 v[102:103], v[70:71], v[70:71], v[98:99] op_sel_hi:[1,1,0]
	v_mul_f32_e32 v98, v72, v72
	v_pk_add_f32 v[100:101], v[100:101], v[100:101] op_sel_hi:[0,1]
	v_pk_fma_f32 v[104:105], v[72:73], v[72:73], v[98:99] op_sel_hi:[1,1,0]
	v_fmamk_f32 v69, v106, 0xb9800000, v69
	v_fmac_f32_e32 v68, 0xb9800000, v106
	v_fmamk_f32 v67, v106, 0xb9800000, v67
	v_fmac_f32_e32 v66, 0xb9800000, v106
	v_mul_f32_e32 v102, v66, v66
	v_mul_f32_e32 v104, v67, v67
	v_mul_f32_e32 v100, v68, v68
	v_mul_f32_e32 v98, v69, v69
	v_pk_add_f32 v[102:103], v[102:103], v[104:105]
	v_pk_add_f32 v[98:99], v[100:101], v[98:99]
	s_nop 0
	v_pk_add_f32 v[98:99], v[102:103], v[98:99]
	s_nop 0
	v_add_f32_e32 v98, v98, v99
	ds_bpermute_b32 v99, v202, v98
	s_waitcnt lgkmcnt(0)
	v_add_f32_e32 v98, v98, v99
	ds_bpermute_b32 v99, v203, v98
	s_waitcnt lgkmcnt(0)
	v_add_f32_e32 v98, v98, v99
	ds_bpermute_b32 v99, v204, v98
	s_waitcnt lgkmcnt(0)
	v_add_f32_e32 v98, v98, v99
	ds_bpermute_b32 v99, v205, v98
	s_waitcnt lgkmcnt(0)
	v_add_f32_e32 v98, v98, v99
	ds_bpermute_b32 v99, v206, v98
	s_waitcnt lgkmcnt(0)
	v_add_f32_e32 v98, v98, v99
	ds_bpermute_b32 v99, v207, v98
	s_waitcnt lgkmcnt(0)
	v_add_f32_e32 v98, v98, v99
	v_fmamk_f32 v98, v98, 0x39800000, v179
	v_mul_f32_e32 v99, 0x4f800000, v98
	v_cmp_gt_f32_e32 vcc, s79, v98
	s_nop 1
	v_cndmask_b32_e32 v98, v98, v99, vcc
	v_sqrt_f32_e32 v99, v98
	s_nop 0
	v_add_u32_e32 v100, -1, v99
	v_fma_f32 v101, -v100, v99, v98
	v_cmp_ge_f32_e64 s[0:1], 0, v101
	v_add_u32_e32 v101, 1, v99
	s_nop 0
	v_cndmask_b32_e64 v100, v99, v100, s[0:1]
	v_fma_f32 v99, -v101, v99, v98
	v_cmp_lt_f32_e64 s[0:1], 0, v99
	s_nop 1
	v_cndmask_b32_e64 v99, v100, v101, s[0:1]
	v_mul_f32_e32 v100, 0x37800000, v99
	v_cndmask_b32_e32 v99, v99, v100, vcc
	v_cmp_class_f32_e32 vcc, v98, v242
	s_nop 1
	v_cndmask_b32_e32 v98, v99, v98, vcc
	v_div_scale_f32 v99, s[0:1], v98, v98, 1.0
	v_rcp_f32_e32 v100, v99
	s_lshl_b64 s[0:1], s[46:47], 12
	s_and_b64 s[8:9], s[48:49], exec
	s_cselect_b32 s2, 0, s2
	v_fma_f32 v101, -v99, v100, 1.0
	v_fmac_f32_e32 v100, v101, v100
	v_div_scale_f32 v101, vcc, 1.0, v98, 1.0
	v_mul_f32_e32 v102, v101, v100
	v_fma_f32 v103, -v99, v102, v101
	v_fmac_f32_e32 v102, v103, v100
	v_fma_f32 v99, -v99, v102, v101
	v_div_fmas_f32 v104, v99, v100, v102
	v_add_u32_e32 v99, s2, v241
	ds_read_b128 v[100:103], v99 offset:49152
	ds_read_b128 v[108:111], v99 offset:50176
	v_div_fixup_f32 v98, v104, v98, 1.0
	ds_read_b128 v[104:107], v99 offset:32768
	ds_read_b128 v[116:119], v99 offset:33792
	v_pk_mul_f32 v[120:121], v[152:153], v[98:99] op_sel_hi:[1,0]
	s_waitcnt lgkmcnt(3)
	v_pk_add_f32 v[100:101], v[100:101], 1.0 op_sel_hi:[1,0]
	v_pk_add_f32 v[102:103], v[102:103], 1.0 op_sel_hi:[1,0]
	s_waitcnt lgkmcnt(1)
	v_pk_fma_f32 v[104:105], v[100:101], v[120:121], v[104:105]
	v_mov_b32_e32 v120, v193
	v_cvt_pk_fp8_f32 v120, v104, v105
	v_pk_mul_f32 v[100:101], v[154:155], v[98:99] op_sel_hi:[1,0]
	v_pk_add_f32 v[108:109], v[108:109], 1.0 op_sel_hi:[1,0]
	v_pk_fma_f32 v[106:107], v[102:103], v[100:101], v[106:107]
	v_lshl_add_u64 v[100:101], v[198:199], 0, s[0:1]
	v_cvt_pk_fp8_f32 v120, v106, v107 op_sel:[0,0,1]
	v_pk_add_f32 v[110:111], v[110:111], 1.0 op_sel_hi:[1,0]
	s_lshl_b64 s[0:1], s[46:47], 13
	v_lshl_add_u64 v[102:103], v[194:195], 0, s[0:1]
	global_store_dword v[100:101], v120, off
	v_bfe_u32 v120, v104, 16, 1
	v_add3_u32 v104, v104, v120, s80
	v_bfe_u32 v120, v105, 16, 1
	v_add3_u32 v105, v105, v120, s80
	v_pk_mul_f32 v[120:121], v[148:149], v[98:99] op_sel_hi:[1,0]
	v_lshrrev_b32_e32 v104, 16, v104
	s_waitcnt lgkmcnt(0)
	v_pk_fma_f32 v[108:109], v[108:109], v[120:121], v[116:117]
	v_mov_b32_e32 v120, v193
	v_cvt_pk_fp8_f32 v120, v108, v109
	v_pk_mul_f32 v[116:117], v[150:151], v[98:99] op_sel_hi:[1,0]
	v_and_or_b32 v104, v105, s76, v104
	v_bfe_u32 v105, v106, 16, 1
	v_pk_fma_f32 v[124:125], v[110:111], v[116:117], v[118:119]
	v_add3_u32 v105, v106, v105, s80
	v_bfe_u32 v106, v107, 16, 1
	v_cvt_pk_fp8_f32 v120, v124, v125 op_sel:[0,0,1]
	v_lshrrev_b32_e32 v105, 16, v105
	v_add3_u32 v106, v107, v106, s80
	v_and_or_b32 v105, v106, s76, v105
	global_store_dwordx2 v[102:103], v[104:105], off sc1
	global_store_dword v[100:101], v120, off offset:256
	v_bfe_u32 v104, v108, 16, 1
	v_add3_u32 v104, v108, v104, s80
	v_bfe_u32 v105, v109, 16, 1
	v_lshrrev_b32_e32 v104, 16, v104
	v_add3_u32 v105, v109, v105, s80
	v_and_or_b32 v126, v105, s76, v104
	v_bfe_u32 v104, v124, 16, 1
	v_add3_u32 v104, v124, v104, s80
	v_lshrrev_b32_e32 v124, 16, v104
	ds_read_b128 v[104:107], v99 offset:51200
	ds_read_b128 v[116:119], v99 offset:52224
	ds_read_b128 v[108:111], v99 offset:34816
	ds_read_b128 v[120:123], v99 offset:35840
	v_pk_mul_f32 v[144:145], v[144:145], v[98:99] op_sel_hi:[1,0]
	s_waitcnt lgkmcnt(3)
	v_pk_add_f32 v[104:105], v[104:105], 1.0 op_sel_hi:[1,0]
	v_bfe_u32 v127, v125, 16, 1
	s_waitcnt lgkmcnt(1)
	v_pk_fma_f32 v[104:105], v[104:105], v[144:145], v[108:109]
	v_pk_mul_f32 v[108:109], v[146:147], v[98:99] op_sel_hi:[1,0]
	v_pk_add_f32 v[106:107], v[106:107], 1.0 op_sel_hi:[1,0]
	v_mov_b32_e32 v144, v193
	v_pk_fma_f32 v[106:107], v[106:107], v[108:109], v[110:111]
	v_add3_u32 v108, v125, v127, s80
	v_and_or_b32 v127, v108, s76, v124
	v_bfe_u32 v108, v104, 16, 1
	v_cvt_pk_fp8_f32 v144, v104, v105
	v_add3_u32 v104, v104, v108, s80
	v_bfe_u32 v108, v105, 16, 1
	v_add3_u32 v105, v105, v108, s80
	v_pk_mul_f32 v[108:109], v[140:141], v[98:99] op_sel_hi:[1,0]
	v_pk_add_f32 v[110:111], v[116:117], 1.0 op_sel_hi:[1,0]
	v_lshrrev_b32_e32 v104, 16, v104
	s_waitcnt lgkmcnt(0)
	v_pk_fma_f32 v[108:109], v[110:111], v[108:109], v[120:121]
	v_mov_b32_e32 v120, v193
	v_cvt_pk_fp8_f32 v120, v108, v109
	v_pk_mul_f32 v[110:111], v[142:143], v[98:99] op_sel_hi:[1,0]
	v_pk_add_f32 v[116:117], v[118:119], 1.0 op_sel_hi:[1,0]
	v_and_or_b32 v104, v105, s76, v104
	v_bfe_u32 v105, v106, 16, 1
	v_pk_fma_f32 v[110:111], v[116:117], v[110:111], v[122:123]
	v_cvt_pk_fp8_f32 v144, v106, v107 op_sel:[0,0,1]
	v_add3_u32 v105, v106, v105, s80
	v_bfe_u32 v106, v107, 16, 1
	v_cvt_pk_fp8_f32 v120, v110, v111 op_sel:[0,0,1]
	v_lshrrev_b32_e32 v105, 16, v105
	v_add3_u32 v106, v107, v106, s80
	v_and_or_b32 v105, v106, s76, v105
	global_store_dwordx2 v[102:103], v[126:127], off offset:512 sc1
	global_store_dword v[100:101], v144, off offset:512
	global_store_dwordx2 v[102:103], v[104:105], off offset:1024 sc1
	global_store_dword v[100:101], v120, off offset:768
	v_bfe_u32 v104, v108, 16, 1
	v_add3_u32 v104, v108, v104, s80
	v_bfe_u32 v105, v109, 16, 1
	v_lshrrev_b32_e32 v104, 16, v104
	v_add3_u32 v105, v109, v105, s80
	v_and_or_b32 v104, v105, s76, v104
	v_bfe_u32 v105, v110, 16, 1
	v_add3_u32 v105, v110, v105, s80
	v_bfe_u32 v106, v111, 16, 1
	v_lshrrev_b32_e32 v105, 16, v105
	v_add3_u32 v106, v111, v106, s80
	v_and_or_b32 v105, v106, s76, v105
	global_store_dwordx2 v[102:103], v[104:105], off offset:1536 sc1
	ds_read_b128 v[104:107], v99 offset:53248
	ds_read_b128 v[108:111], v99 offset:36864
	v_pk_mul_f32 v[124:125], v[136:137], v[98:99] op_sel_hi:[1,0]
	ds_read_b128 v[116:119], v99 offset:54272
	ds_read_b128 v[120:123], v99 offset:37888
	s_waitcnt lgkmcnt(3)
	v_pk_add_f32 v[104:105], v[104:105], 1.0 op_sel_hi:[1,0]
	v_pk_add_f32 v[106:107], v[106:107], 1.0 op_sel_hi:[1,0]
	s_waitcnt lgkmcnt(2)
	v_pk_fma_f32 v[104:105], v[104:105], v[124:125], v[108:109]
	v_mov_b32_e32 v124, v193
	v_cvt_pk_fp8_f32 v124, v104, v105
	v_pk_mul_f32 v[108:109], v[138:139], v[98:99] op_sel_hi:[1,0]
	v_pk_mul_f32 v[128:129], v[128:129], v[98:99] op_sel_hi:[1,0]
	v_pk_fma_f32 v[106:107], v[106:107], v[108:109], v[110:111]
	v_bfe_u32 v108, v104, 16, 1
	v_add3_u32 v104, v104, v108, s80
	v_bfe_u32 v108, v105, 16, 1
	v_add3_u32 v105, v105, v108, s80
	v_pk_mul_f32 v[108:109], v[132:133], v[98:99] op_sel_hi:[1,0]
	s_waitcnt lgkmcnt(1)
	v_pk_add_f32 v[110:111], v[116:117], 1.0 op_sel_hi:[1,0]
	v_cvt_pk_fp8_f32 v124, v106, v107 op_sel:[0,0,1]
	s_waitcnt lgkmcnt(0)
	v_pk_fma_f32 v[108:109], v[108:109], v[110:111], v[120:121]
	v_mov_b32_e32 v120, v193
	v_cvt_pk_fp8_f32 v120, v108, v109
	v_lshrrev_b32_e32 v104, 16, v104
	v_pk_mul_f32 v[110:111], v[134:135], v[98:99] op_sel_hi:[1,0]
	v_pk_add_f32 v[116:117], v[118:119], 1.0 op_sel_hi:[1,0]
	global_store_dword v[100:101], v124, off offset:1024
	v_and_or_b32 v104, v105, s76, v104
	v_bfe_u32 v105, v106, 16, 1
	v_pk_fma_f32 v[124:125], v[110:111], v[116:117], v[122:123]
	v_add3_u32 v105, v106, v105, s80
	v_bfe_u32 v106, v107, 16, 1
	v_cvt_pk_fp8_f32 v120, v124, v125 op_sel:[0,0,1]
	v_lshrrev_b32_e32 v105, 16, v105
	v_add3_u32 v106, v107, v106, s80
	v_and_or_b32 v105, v106, s76, v105
	global_store_dwordx2 v[102:103], v[104:105], off offset:2048 sc1
	global_store_dword v[100:101], v120, off offset:1280
	v_bfe_u32 v104, v108, 16, 1
	v_add3_u32 v104, v108, v104, s80
	v_bfe_u32 v105, v109, 16, 1
	v_lshrrev_b32_e32 v104, 16, v104
	v_add3_u32 v105, v109, v105, s80
	v_and_or_b32 v126, v105, s76, v104
	v_bfe_u32 v104, v124, 16, 1
	v_add3_u32 v104, v124, v104, s80
	v_lshrrev_b32_e32 v124, 16, v104
	ds_read_b128 v[104:107], v99 offset:55296
	ds_read_b128 v[116:119], v99 offset:56320
	ds_read_b128 v[108:111], v99 offset:38912
	ds_read_b128 v[120:123], v99 offset:39936
	v_bfe_u32 v127, v125, 16, 1
	s_waitcnt lgkmcnt(3)
	v_pk_add_f32 v[104:105], v[104:105], 1.0 op_sel_hi:[1,0]
	v_pk_add_f32 v[106:107], v[106:107], 1.0 op_sel_hi:[1,0]
	s_waitcnt lgkmcnt(1)
	v_pk_fma_f32 v[104:105], v[128:129], v[104:105], v[108:109]
	v_pk_mul_f32 v[108:109], v[130:131], v[98:99] op_sel_hi:[1,0]
	v_mov_b32_e32 v128, v193
	v_pk_fma_f32 v[106:107], v[108:109], v[106:107], v[110:111]
	v_add3_u32 v108, v125, v127, s80
	v_and_or_b32 v127, v108, s76, v124
	v_bfe_u32 v108, v104, 16, 1
	v_cvt_pk_fp8_f32 v128, v104, v105
	v_add3_u32 v104, v104, v108, s80
	v_bfe_u32 v108, v105, 16, 1
	v_add3_u32 v105, v105, v108, s80
	v_pk_mul_f32 v[108:109], v[112:113], v[98:99] op_sel_hi:[1,0]
	v_pk_add_f32 v[110:111], v[116:117], 1.0 op_sel_hi:[1,0]
	v_mov_b32_e32 v116, v193
	s_waitcnt lgkmcnt(0)
	v_pk_fma_f32 v[108:109], v[108:109], v[110:111], v[120:121]
	v_lshrrev_b32_e32 v104, 16, v104
	v_cvt_pk_fp8_f32 v116, v108, v109
	v_pk_mul_f32 v[110:111], v[114:115], v[98:99] op_sel_hi:[1,0]
	v_pk_add_f32 v[112:113], v[118:119], 1.0 op_sel_hi:[1,0]
	v_and_or_b32 v104, v105, s76, v104
	v_bfe_u32 v105, v106, 16, 1
	v_pk_fma_f32 v[110:111], v[110:111], v[112:113], v[122:123]
	v_cvt_pk_fp8_f32 v128, v106, v107 op_sel:[0,0,1]
	v_add3_u32 v105, v106, v105, s80
	v_bfe_u32 v106, v107, 16, 1
	v_cvt_pk_fp8_f32 v116, v110, v111 op_sel:[0,0,1]
	v_lshrrev_b32_e32 v105, 16, v105
	v_add3_u32 v106, v107, v106, s80
	v_and_or_b32 v105, v106, s76, v105
	global_store_dwordx2 v[102:103], v[126:127], off offset:2560 sc1
	global_store_dword v[100:101], v128, off offset:1536
	global_store_dwordx2 v[102:103], v[104:105], off offset:3072 sc1
	global_store_dword v[100:101], v116, off offset:1792
	v_bfe_u32 v104, v108, 16, 1
	v_add3_u32 v104, v108, v104, s80
	v_bfe_u32 v105, v109, 16, 1
	v_lshrrev_b32_e32 v104, 16, v104
	v_add3_u32 v105, v109, v105, s80
	v_and_or_b32 v104, v105, s76, v104
	v_bfe_u32 v105, v110, 16, 1
	v_add3_u32 v105, v110, v105, s80
	v_bfe_u32 v106, v111, 16, 1
	v_lshrrev_b32_e32 v105, 16, v105
	v_add3_u32 v106, v111, v106, s80
	v_and_or_b32 v105, v106, s76, v105
	global_store_dwordx2 v[102:103], v[104:105], off offset:3584 sc1
	ds_read_b128 v[104:107], v99 offset:57344
	ds_read_b128 v[108:111], v99 offset:40960
	v_pk_mul_f32 v[94:95], v[94:95], v[98:99] op_sel_hi:[1,0]
	v_pk_mul_f32 v[96:97], v[96:97], v[98:99] op_sel_hi:[1,0]
	ds_read_b128 v[112:115], v99 offset:58368
	ds_read_b128 v[116:119], v99 offset:41984
	s_waitcnt lgkmcnt(3)
	v_pk_add_f32 v[104:105], v[104:105], 1.0 op_sel_hi:[1,0]
	v_pk_mul_f32 v[90:91], v[90:91], v[98:99] op_sel_hi:[1,0]
	s_waitcnt lgkmcnt(2)
	v_pk_fma_f32 v[94:95], v[94:95], v[104:105], v[108:109]
	v_mov_b32_e32 v108, v193
	v_pk_add_f32 v[104:105], v[106:107], 1.0 op_sel_hi:[1,0]
	v_cvt_pk_fp8_f32 v108, v94, v95
	v_pk_fma_f32 v[96:97], v[96:97], v[104:105], v[110:111]
	v_bfe_u32 v104, v94, 16, 1
	v_add3_u32 v94, v94, v104, s80
	v_bfe_u32 v104, v95, 16, 1
	v_lshrrev_b32_e32 v94, 16, v94
	v_add3_u32 v95, v95, v104, s80
	v_and_or_b32 v94, v95, s76, v94
	v_bfe_u32 v95, v96, 16, 1
	v_cvt_pk_fp8_f32 v108, v96, v97 op_sel:[0,0,1]
	v_add3_u32 v95, v96, v95, s80
	v_bfe_u32 v96, v97, 16, 1
	v_lshrrev_b32_e32 v95, 16, v95
	v_add3_u32 v96, v97, v96, s80
	v_and_or_b32 v95, v96, s76, v95
	s_waitcnt lgkmcnt(1)
	v_pk_add_f32 v[96:97], v[112:113], 1.0 op_sel_hi:[1,0]
	v_mov_b32_e32 v104, v193
	s_waitcnt lgkmcnt(0)
	v_pk_fma_f32 v[96:97], v[90:91], v[96:97], v[116:117]
	v_pk_mul_f32 v[90:91], v[92:93], v[98:99] op_sel_hi:[1,0]
	v_cvt_pk_fp8_f32 v104, v96, v97
	v_pk_add_f32 v[92:93], v[114:115], 1.0 op_sel_hi:[1,0]
	global_store_dword v[100:101], v108, off offset:2048
	v_pk_fma_f32 v[114:115], v[90:91], v[92:93], v[118:119]
	v_bfe_u32 v92, v96, 16, 1
	v_cvt_pk_fp8_f32 v104, v114, v115 op_sel:[0,0,1]
	v_add3_u32 v92, v96, v92, s80
	v_bfe_u32 v93, v97, 16, 1
	v_add_co_u32_e32 v90, vcc, s77, v102
	v_lshrrev_b32_e32 v92, 16, v92
	v_add3_u32 v93, v97, v93, s80
	v_addc_co_u32_e32 v91, vcc, 0, v103, vcc
	v_and_or_b32 v96, v93, s76, v92
	v_bfe_u32 v92, v114, 16, 1
	global_store_dwordx2 v[90:91], v[94:95], off sc1
	global_store_dword v[100:101], v104, off offset:2304
	v_add3_u32 v92, v114, v92, s80
	v_lshrrev_b32_e32 v97, 16, v92
	ds_read_b128 v[92:95], v99 offset:59392
	ds_read_b128 v[106:109], v99 offset:60416
	ds_read_b128 v[102:105], v99 offset:43008
	ds_read_b128 v[110:113], v99 offset:44032
	v_pk_mul_f32 v[86:87], v[86:87], v[98:99] op_sel_hi:[1,0]
	s_waitcnt lgkmcnt(3)
	v_pk_add_f32 v[92:93], v[92:93], 1.0 op_sel_hi:[1,0]
	v_bfe_u32 v114, v115, 16, 1
	s_waitcnt lgkmcnt(1)
	v_pk_fma_f32 v[86:87], v[86:87], v[92:93], v[102:103]
	v_pk_mul_f32 v[88:89], v[88:89], v[98:99] op_sel_hi:[1,0]
	v_pk_add_f32 v[92:93], v[94:95], 1.0 op_sel_hi:[1,0]
	v_mov_b32_e32 v102, v193
	v_pk_fma_f32 v[88:89], v[88:89], v[92:93], v[104:105]
	v_add3_u32 v92, v115, v114, s80
	v_and_or_b32 v97, v92, s76, v97
	v_bfe_u32 v92, v86, 16, 1
	v_cvt_pk_fp8_f32 v102, v86, v87
	v_add3_u32 v86, v86, v92, s80
	v_bfe_u32 v92, v87, 16, 1
	v_add3_u32 v87, v87, v92, s80
	v_pk_mul_f32 v[82:83], v[82:83], v[98:99] op_sel_hi:[1,0]
	v_pk_add_f32 v[92:93], v[106:107], 1.0 op_sel_hi:[1,0]
	v_mov_b32_e32 v94, v193
	s_waitcnt lgkmcnt(0)
	v_pk_fma_f32 v[82:83], v[82:83], v[92:93], v[110:111]
	v_lshrrev_b32_e32 v86, 16, v86
	v_cvt_pk_fp8_f32 v94, v82, v83
	v_pk_mul_f32 v[84:85], v[84:85], v[98:99] op_sel_hi:[1,0]
	v_pk_add_f32 v[92:93], v[108:109], 1.0 op_sel_hi:[1,0]
	v_and_or_b32 v86, v87, s76, v86
	v_bfe_u32 v87, v88, 16, 1
	v_pk_fma_f32 v[84:85], v[84:85], v[92:93], v[112:113]
	v_cvt_pk_fp8_f32 v102, v88, v89 op_sel:[0,0,1]
	v_add3_u32 v87, v88, v87, s80
	v_bfe_u32 v88, v89, 16, 1
	v_cvt_pk_fp8_f32 v94, v84, v85 op_sel:[0,0,1]
	v_lshrrev_b32_e32 v87, 16, v87
	v_add3_u32 v88, v89, v88, s80
	v_and_or_b32 v87, v88, s76, v87
	global_store_dwordx2 v[90:91], v[96:97], off offset:512 sc1
	global_store_dword v[100:101], v102, off offset:2560
	global_store_dwordx2 v[90:91], v[86:87], off offset:1024 sc1
	global_store_dword v[100:101], v94, off offset:2816
	v_bfe_u32 v86, v82, 16, 1
	v_add3_u32 v82, v82, v86, s80
	v_bfe_u32 v86, v83, 16, 1
	v_lshrrev_b32_e32 v82, 16, v82
	v_add3_u32 v83, v83, v86, s80
	v_and_or_b32 v82, v83, s76, v82
	v_bfe_u32 v83, v84, 16, 1
	v_add3_u32 v83, v84, v83, s80
	v_bfe_u32 v84, v85, 16, 1
	v_lshrrev_b32_e32 v83, 16, v83
	v_add3_u32 v84, v85, v84, s80
	v_and_or_b32 v83, v84, s76, v83
	global_store_dwordx2 v[90:91], v[82:83], off offset:1536 sc1
	ds_read_b128 v[82:85], v99 offset:61440
	ds_read_b128 v[86:89], v99 offset:45056
	ds_read_b128 v[92:95], v99 offset:62464
	ds_read_b128 v[102:105], v99 offset:46080
	v_pk_mul_f32 v[78:79], v[78:79], v[98:99] op_sel_hi:[1,0]
	s_waitcnt lgkmcnt(3)
	v_pk_add_f32 v[82:83], v[82:83], 1.0 op_sel_hi:[1,0]
	v_pk_mul_f32 v[80:81], v[80:81], v[98:99] op_sel_hi:[1,0]
	s_waitcnt lgkmcnt(2)
	v_pk_fma_f32 v[78:79], v[78:79], v[82:83], v[86:87]
	v_pk_add_f32 v[82:83], v[84:85], 1.0 op_sel_hi:[1,0]
	v_mov_b32_e32 v86, v193
	v_pk_fma_f32 v[80:81], v[80:81], v[82:83], v[88:89]
	v_bfe_u32 v82, v78, 16, 1
	v_cvt_pk_fp8_f32 v86, v78, v79
	v_add3_u32 v78, v78, v82, s80
	v_bfe_u32 v82, v79, 16, 1
	v_add3_u32 v79, v79, v82, s80
	v_pk_mul_f32 v[74:75], v[74:75], v[98:99] op_sel_hi:[1,0]
	s_waitcnt lgkmcnt(1)
	v_pk_add_f32 v[82:83], v[92:93], 1.0 op_sel_hi:[1,0]
	v_lshrrev_b32_e32 v78, 16, v78
	s_waitcnt lgkmcnt(0)
	v_pk_fma_f32 v[74:75], v[74:75], v[82:83], v[102:103]
	v_mov_b32_e32 v84, v193
	v_and_or_b32 v78, v79, s76, v78
	v_bfe_u32 v79, v80, 16, 1
	v_cvt_pk_fp8_f32 v84, v74, v75
	v_cvt_pk_fp8_f32 v86, v80, v81 op_sel:[0,0,1]
	v_add3_u32 v79, v80, v79, s80
	v_bfe_u32 v80, v81, 16, 1
	v_pk_mul_f32 v[76:77], v[76:77], v[98:99] op_sel_hi:[1,0]
	v_pk_add_f32 v[82:83], v[94:95], 1.0 op_sel_hi:[1,0]
	v_lshrrev_b32_e32 v79, 16, v79
	v_pk_fma_f32 v[92:93], v[76:77], v[82:83], v[104:105]
	v_add3_u32 v76, v81, v80, s80
	v_and_or_b32 v79, v76, s76, v79
	v_bfe_u32 v76, v74, 16, 1
	v_cvt_pk_fp8_f32 v84, v92, v93 op_sel:[0,0,1]
	v_add3_u32 v74, v74, v76, s80
	v_bfe_u32 v76, v75, 16, 1
	v_lshrrev_b32_e32 v74, 16, v74
	v_add3_u32 v75, v75, v76, s80
	v_and_or_b32 v94, v75, s76, v74
	v_bfe_u32 v74, v92, 16, 1
	global_store_dword v[100:101], v86, off offset:3072
	global_store_dwordx2 v[90:91], v[78:79], off offset:2048 sc1
	global_store_dword v[100:101], v84, off offset:3328
	v_add3_u32 v74, v92, v74, s80
	v_lshrrev_b32_e32 v92, 16, v74
	ds_read_b128 v[74:77], v99 offset:63488
	ds_read_b128 v[82:85], v99 offset:64512
	ds_read_b128 v[78:81], v99 offset:47104
	ds_read_b128 v[86:89], v99 offset:48128
	v_pk_mul_f32 v[70:71], v[70:71], v[98:99] op_sel_hi:[1,0]
	s_waitcnt lgkmcnt(3)
	v_pk_add_f32 v[74:75], v[74:75], 1.0 op_sel_hi:[1,0]
	v_bfe_u32 v95, v93, 16, 1
	s_waitcnt lgkmcnt(1)
	v_pk_fma_f32 v[70:71], v[70:71], v[74:75], v[78:79]
	v_pk_mul_f32 v[72:73], v[72:73], v[98:99] op_sel_hi:[1,0]
	v_pk_add_f32 v[74:75], v[76:77], 1.0 op_sel_hi:[1,0]
	v_mov_b32_e32 v78, v193
	v_pk_fma_f32 v[72:73], v[72:73], v[74:75], v[80:81]
	v_add3_u32 v74, v93, v95, s80
	v_and_or_b32 v95, v74, s76, v92
	v_bfe_u32 v74, v70, 16, 1
	v_cvt_pk_fp8_f32 v78, v70, v71
	v_add3_u32 v70, v70, v74, s80
	v_bfe_u32 v74, v71, 16, 1
	v_add3_u32 v71, v71, v74, s80
	v_pk_mul_f32 v[66:67], v[66:67], v[98:99] op_sel_hi:[1,0]
	v_pk_add_f32 v[74:75], v[82:83], 1.0 op_sel_hi:[1,0]
	v_mov_b32_e32 v76, v193
	s_waitcnt lgkmcnt(0)
	v_pk_fma_f32 v[66:67], v[66:67], v[74:75], v[86:87]
	v_lshrrev_b32_e32 v70, 16, v70
	v_cvt_pk_fp8_f32 v76, v66, v67
	v_pk_mul_f32 v[68:69], v[68:69], v[98:99] op_sel_hi:[1,0]
	v_pk_add_f32 v[74:75], v[84:85], 1.0 op_sel_hi:[1,0]
	v_and_or_b32 v70, v71, s76, v70
	v_bfe_u32 v71, v72, 16, 1
	v_pk_fma_f32 v[68:69], v[68:69], v[74:75], v[88:89]
	v_cvt_pk_fp8_f32 v78, v72, v73 op_sel:[0,0,1]
	v_add3_u32 v71, v72, v71, s80
	v_bfe_u32 v72, v73, 16, 1
	v_cvt_pk_fp8_f32 v76, v68, v69 op_sel:[0,0,1]
	v_lshrrev_b32_e32 v71, 16, v71
	v_add3_u32 v72, v73, v72, s80
	v_and_or_b32 v71, v72, s76, v71
	global_store_dwordx2 v[90:91], v[94:95], off offset:2560 sc1
	global_store_dword v[100:101], v78, off offset:3584
	global_store_dwordx2 v[90:91], v[70:71], off offset:3072 sc1
	global_store_dword v[100:101], v76, off offset:3840
	v_bfe_u32 v70, v66, 16, 1
	v_add3_u32 v66, v66, v70, s80
	v_bfe_u32 v70, v67, 16, 1
	v_lshrrev_b32_e32 v66, 16, v66
	v_add3_u32 v67, v67, v70, s80
	v_and_or_b32 v66, v67, s76, v66
	v_bfe_u32 v67, v68, 16, 1
	v_add3_u32 v67, v68, v67, s80
	v_bfe_u32 v68, v69, 16, 1
	v_lshrrev_b32_e32 v67, 16, v67
	v_add3_u32 v68, v69, v68, s80
	v_and_or_b32 v67, v68, s76, v67
	global_store_dwordx2 v[90:91], v[66:67], off offset:3584 sc1
	s_add_u32 s26, s26, s34
	s_addc_u32 s27, s27, s35
	s_add_u32 s4, s4, s6
	s_addc_u32 s5, s5, s7
	s_add_i32 s69, s69, s74
	s_andn2_b64 vcc, exec, s[52:53]
	s_mov_b32 s46, s50
	s_cbranch_vccz .LBB0_374
